# ctx rows skipped in last layer C0-C4 + C0 loop hoist + S5 counted waits with RWKV prio 3 S5 prio 2
# speedup vs baseline: 1.0563x; 1.0125x over previous
; DI bool swz_tile(int i, int NC, int& rt, int& ct) {
;   const int G = gridDim.x;
;   if ((G & 7) == 0) {
;     const int x = blockIdx.x & 7, j = blockIdx.x >> 3, per = G >> 3;
;     const int T8 = NROWT * NC / 8;
;     const int ul = i * per + j;
;     if (ul >= T8) return false;
;     const int u = x * T8 + ul;
;     const int band = u / (8 * NC), rem = u % (8 * NC);
;     ct = rem >> 3; rt = band * 8 + (rem & 7);
;     return true;
;   }
.LBB0_44:
	s_mul_i32 s6, s9, s8
	v_readlane_b32 s4, v254, 18
	s_add_i32 s6, s6, s4
	v_readlane_b32 s4, v253, 2
	s_cmp_ge_i32 s4, 29
	s_cselect_b32 s4, 64, 0
	s_sub_i32 s4, 0x43f, s4
	s_cmp_gt_i32 s6, s4
	s_mov_b64 s[4:5], 0
	s_cbranch_scc1 .LBB0_46
	v_readlane_b32 s4, v254, 19
	v_readlane_b32 s5, v253, 2
	s_cmp_ge_i32 s5, 29
	s_cbranch_scc0 .Lctxsw0_a
	v_readlane_b32 s4, v254, 36
	s_and_b32 s4, s4, 7
	s_lshl_b32 s4, s4, 10
.Lctxsw0_a:
	s_add_i32 s4, s6, s4
	s_ashr_i32 s5, s4, 31
	s_lshr_b32 s5, s5, 24
	s_add_i32 s5, s4, s5
	s_ashr_i32 s6, s5, 8
	s_and_b32 s5, s5, 0xffffff00
	s_sub_i32 s4, s4, s5
	s_ashr_i32 s11, s4, 3
	s_lshl_b32 s5, s6, 3
	s_and_b32 s4, s4, 7
	s_or_b32 s10, s4, s5
	v_readlane_b32 s5, v253, 2
	s_cmp_ge_i32 s5, 29
	s_cbranch_scc0 .Lctxsw0_b
	s_lshr_b32 s5, s10, 5
	s_lshl_b32 s5, s5, 1
	s_add_i32 s10, s10, s5
	s_add_i32 s10, s10, 2
.Lctxsw0_b:
	s_mov_b64 s[4:5], -1
.LBB0_46:
	s_mov_b32 s86, s10
	s_mov_b32 s74, s11
	s_andn2_b64 vcc, exec, s[4:5]
	s_mov_b64 s[4:5], -1
	s_cbranch_vccz .LBB0_34

; DI bool swz_tile(int i, int NC, int& rt, int& ct) {
;   const int G = gridDim.x;
;   if ((G & 7) == 0) {
;     const int x = blockIdx.x & 7, j = blockIdx.x >> 3, per = G >> 3;
;     const int T8 = NROWT * NC / 8;
;     const int ul = i * per + j;
;     if (ul >= T8) return false;
;     const int u = x * T8 + ul;
;     const int band = u / (8 * NC), rem = u % (8 * NC);
;     ct = rem >> 3; rt = band * 8 + (rem & 7);
;     return true;
;   }
.LBB0_158:
	s_mul_i32 s6, s78, s77
	v_readlane_b32 s4, v254, 18
	s_add_i32 s6, s6, s4
	v_readlane_b32 s4, v253, 2
	s_cmp_ge_i32 s4, 29
	s_cselect_b32 s4, 16, 0
	s_sub_i32 s4, 0x10f, s4
	s_cmp_gt_i32 s6, s4
	s_mov_b64 s[4:5], 0
	s_cbranch_scc1 .LBB0_160
	v_readlane_b32 s2, v254, 26
	v_readlane_b32 s5, v253, 2
	s_cmp_ge_i32 s5, 29
	s_cbranch_scc0 .Lctxsw1_a
	v_readlane_b32 s2, v254, 36
	s_and_b32 s2, s2, 7
	s_lshl_b32 s2, s2, 8
.Lctxsw1_a:
	s_add_i32 s2, s6, s2
	s_ashr_i32 s4, s2, 31
	s_lshr_b32 s4, s4, 26
	s_add_i32 s4, s2, s4
	s_ashr_i32 s5, s4, 6
	s_andn2_b32 s4, s4, 63
	s_sub_i32 s4, s2, s4
	s_ashr_i32 s2, s4, 3
	s_lshl_b32 s5, s5, 3
	s_and_b32 s4, s4, 7
	s_or_b32 s8, s4, s5
	v_readlane_b32 s5, v253, 2
	s_cmp_ge_i32 s5, 29
	s_cbranch_scc0 .Lctxsw1_b
	s_lshr_b32 s5, s8, 5
	s_lshl_b32 s5, s5, 1
	s_add_i32 s8, s8, s5
	s_add_i32 s8, s8, 2
.Lctxsw1_b:
	s_mov_b64 s[4:5], -1
.LBB0_160:
	s_mov_b32 s79, s2
	s_mov_b32 s76, s8
	s_andn2_b64 vcc, exec, s[4:5]
	s_mov_b64 s[4:5], -1
	s_cbranch_vccz .LBB0_77

; DI bool swz_tile(int i, int NC, int& rt, int& ct) {
;   const int G = gridDim.x;
;   if ((G & 7) == 0) {
;     const int x = blockIdx.x & 7, j = blockIdx.x >> 3, per = G >> 3;
;     const int T8 = NROWT * NC / 8;
;     const int ul = i * per + j;
;     if (ul >= T8) return false;
;     const int u = x * T8 + ul;
;     const int band = u / (8 * NC), rem = u % (8 * NC);
;     ct = rem >> 3; rt = band * 8 + (rem & 7);
;     return true;
;   }
.LBB0_195:
	s_mul_i32 s4, s86, s80
	v_readlane_b32 s0, v254, 18
	s_add_i32 s4, s4, s0
	v_readlane_b32 s0, v253, 2
	s_cmp_ge_i32 s0, 29
	s_cselect_b32 s0, 16, 0
	s_sub_i32 s0, 0x10f, s0
	s_cmp_gt_i32 s4, s0
	s_mov_b64 s[0:1], 0
	s_cbranch_scc1 .LBB0_197
	v_readlane_b32 s0, v254, 26
	v_readlane_b32 s1, v253, 2
	s_cmp_ge_i32 s1, 29
	s_cbranch_scc0 .Lctxsw2_a
	v_readlane_b32 s0, v254, 36
	s_and_b32 s0, s0, 7
	s_lshl_b32 s0, s0, 8
.Lctxsw2_a:
	s_add_i32 s0, s4, s0
	s_ashr_i32 s1, s0, 31
	s_lshr_b32 s1, s1, 26
	s_add_i32 s1, s0, s1
	s_ashr_i32 s4, s1, 6
	s_andn2_b32 s1, s1, 63
	s_sub_i32 s0, s0, s1
	s_ashr_i32 s2, s0, 3
	s_lshl_b32 s1, s4, 3
	s_and_b32 s0, s0, 7
	s_or_b32 s6, s0, s1
	v_readlane_b32 s1, v253, 2
	s_cmp_ge_i32 s1, 29
	s_cbranch_scc0 .Lctxsw2_b
	s_lshr_b32 s1, s6, 5
	s_lshl_b32 s1, s1, 1
	s_add_i32 s6, s6, s1
	s_add_i32 s6, s6, 2
.Lctxsw2_b:
	s_mov_b64 s[0:1], -1
.LBB0_197:
	s_mov_b32 s75, s2
	s_mov_b32 s77, s6
	s_andn2_b64 vcc, exec, s[0:1]
	s_mov_b64 s[0:1], -1
	s_cbranch_vccz .LBB0_168

; DI void phaseC0_tile(const Params& p, int l, int t, char* smem) {
;     ...
;       const int hd = col0 >> 6;
;       const u16* y0 = p.R2 + (size_t)R * 512 + col0;
;       const u16* y1 = y0 + (size_t)NTOK * 512;
;       float s0 = 0.f, s1 = 0.f;
; #pragma unroll 1
;       for (int c8 = 0; c8 < 4; ++c8) {
;         float a[8], bq[8];
;         unpack8(*(const uint4*)(y0 + 8 * c8), a);
;         unpack8(*(const uint4*)(y1 + 8 * c8), bq);
; #pragma unroll
;         for (int i = 0; i < 8; ++i) { float y = a[i] + bq[i]; s0 += y; s1 += y * y; }
;       }
.LBB0_347:
	s_or_b64 exec, exec, s[4:5]
	v_lshl_add_u32 v64, s2, 6, v146
	v_mad_i64_i32 v[100:101], s[4:5], v64, s81, 0
	s_andn2_b64 vcc, exec, s[92:93]
	s_mov_b64 s[4:5], -1
	s_waitcnt lgkmcnt(0)
	s_barrier
	s_cbranch_vccnz .LBB0_369
	v_ashrrev_i32_e32 v65, 31, v64
	v_lshlrev_b64 v[66:67], 10, v[64:65]
	v_lshl_add_u64 v[102:103], v[86:87], 0, v[66:67]
	global_load_dwordx4 v[184:187], v[102:103], off
	global_load_dwordx4 v[188:191], v[102:103], off offset:16
	global_load_dwordx4 v[198:201], v[102:103], off offset:32
	global_load_dwordx4 v[202:205], v[102:103], off offset:48
	v_add_co_u32_e32 v192, vcc, 0x2200000, v102
	s_nop 1
	v_addc_co_u32_e32 v193, vcc, 0, v103, vcc
	global_load_dwordx4 v[206:209], v[192:193], off
	global_load_dwordx4 v[210:213], v[192:193], off offset:16
	global_load_dwordx4 v[224:227], v[192:193], off offset:32
	global_load_dwordx4 v[234:237], v[192:193], off offset:48
	v_mov_b32_e32 v67, 0
	s_mov_b64 s[6:7], 0
	v_mov_b32_e32 v66, v67
.LBB0_349:
	s_waitcnt vmcnt(0)
	v_lshlrev_b32_e32 v75, 16, v184
	v_and_b32_e32 v74, 0xffff0000, v184
	v_lshlrev_b32_e32 v77, 16, v185
	v_and_b32_e32 v76, 0xffff0000, v185
	v_lshlrev_b32_e32 v79, 16, v186
	v_and_b32_e32 v78, 0xffff0000, v186
	v_lshlrev_b32_e32 v81, 16, v187
	v_and_b32_e32 v80, 0xffff0000, v187
	v_lshlrev_b32_e32 v73, 16, v206
	v_and_b32_e32 v72, 0xffff0000, v206
	v_lshlrev_b32_e32 v83, 16, v207
	v_and_b32_e32 v82, 0xffff0000, v207
	v_lshlrev_b32_e32 v69, 16, v208
	v_and_b32_e32 v68, 0xffff0000, v208
	v_lshlrev_b32_e32 v85, 16, v209
	v_and_b32_e32 v84, 0xffff0000, v209
	v_pk_add_f32 v[70:71], v[74:75], v[72:73]
	v_mov_b32_e32 v74, v80
	v_pk_mul_f32 v[72:73], v[70:71], v[70:71]
	v_add_f32_e32 v67, v67, v71
	v_add_f32_e32 v66, v66, v73
	v_add_f32_e32 v70, v70, v67
	v_add_f32_e32 v72, v72, v66
	v_pk_add_f32 v[66:67], v[76:77], v[82:83]
	s_nop 0
	v_add_f32_e32 v73, v67, v70
	v_pk_mul_f32 v[70:71], v[66:67], v[66:67]
	s_nop 0
	v_add_f32_e32 v67, v71, v72
	v_add_f32_e32 v71, v66, v73
	v_add_f32_e32 v70, v70, v67
	v_pk_add_f32 v[66:67], v[78:79], v[68:69]
	s_nop 0
	v_pk_mul_f32 v[68:69], v[66:67], v[66:67]
	v_add_f32_e32 v76, v67, v71
	v_add_f32_e32 v67, v69, v70
	v_pk_add_f32 v[70:71], v[80:81], v[84:85]
	v_mov_b32_e32 v75, v66
	v_pk_mul_f32 v[72:73], v[70:71], v[70:71]
	v_mov_b32_e32 v85, v76
	v_add_f32_e32 v68, v68, v67
	v_pk_add_f32 v[66:67], v[74:75], v[84:85]
	v_pk_mov_b32 v[72:73], v[72:73], v[80:81] op_sel:[1,0]
	v_mov_b32_e32 v69, v84
	v_pk_add_f32 v[68:69], v[72:73], v[68:69]
	v_pk_mul_f32 v[72:73], v[70:71], v[66:67]
	v_pk_add_f32 v[66:67], v[70:71], v[66:67]
	s_nop 0
	v_mov_b32_e32 v73, v67
	v_pk_add_f32 v[66:67], v[72:73], v[68:69]
	v_lshlrev_b32_e32 v75, 16, v188
	v_and_b32_e32 v74, 0xffff0000, v188
	v_lshlrev_b32_e32 v77, 16, v189
	v_and_b32_e32 v76, 0xffff0000, v189
	v_lshlrev_b32_e32 v79, 16, v190
	v_and_b32_e32 v78, 0xffff0000, v190
	v_lshlrev_b32_e32 v81, 16, v191
	v_and_b32_e32 v80, 0xffff0000, v191
	v_lshlrev_b32_e32 v73, 16, v210
	v_and_b32_e32 v72, 0xffff0000, v210
	v_lshlrev_b32_e32 v83, 16, v211
	v_and_b32_e32 v82, 0xffff0000, v211
	v_lshlrev_b32_e32 v69, 16, v212
	v_and_b32_e32 v68, 0xffff0000, v212
	v_lshlrev_b32_e32 v85, 16, v213
	v_and_b32_e32 v84, 0xffff0000, v213
	v_pk_add_f32 v[70:71], v[74:75], v[72:73]
	v_mov_b32_e32 v74, v80
	v_pk_mul_f32 v[72:73], v[70:71], v[70:71]
	v_add_f32_e32 v67, v67, v71
	v_add_f32_e32 v66, v66, v73
	v_add_f32_e32 v70, v70, v67
	v_add_f32_e32 v72, v72, v66
	v_pk_add_f32 v[66:67], v[76:77], v[82:83]
	s_nop 0
	v_add_f32_e32 v73, v67, v70
	v_pk_mul_f32 v[70:71], v[66:67], v[66:67]
	s_nop 0
	v_add_f32_e32 v67, v71, v72
	v_add_f32_e32 v71, v66, v73
	v_add_f32_e32 v70, v70, v67
	v_pk_add_f32 v[66:67], v[78:79], v[68:69]
	s_nop 0
	v_pk_mul_f32 v[68:69], v[66:67], v[66:67]
	v_add_f32_e32 v76, v67, v71
	v_add_f32_e32 v67, v69, v70
	v_pk_add_f32 v[70:71], v[80:81], v[84:85]
	v_mov_b32_e32 v75, v66
	v_pk_mul_f32 v[72:73], v[70:71], v[70:71]
	v_mov_b32_e32 v85, v76
	v_add_f32_e32 v68, v68, v67
	v_pk_add_f32 v[66:67], v[74:75], v[84:85]
	v_pk_mov_b32 v[72:73], v[72:73], v[80:81] op_sel:[1,0]
	v_mov_b32_e32 v69, v84
	v_pk_add_f32 v[68:69], v[72:73], v[68:69]
	v_pk_mul_f32 v[72:73], v[70:71], v[66:67]
	v_pk_add_f32 v[66:67], v[70:71], v[66:67]
	s_nop 0
	v_mov_b32_e32 v73, v67
	v_pk_add_f32 v[66:67], v[72:73], v[68:69]
	v_lshlrev_b32_e32 v75, 16, v198
	v_and_b32_e32 v74, 0xffff0000, v198
	v_lshlrev_b32_e32 v77, 16, v199
	v_and_b32_e32 v76, 0xffff0000, v199
	v_lshlrev_b32_e32 v79, 16, v200
	v_and_b32_e32 v78, 0xffff0000, v200
	v_lshlrev_b32_e32 v81, 16, v201
	v_and_b32_e32 v80, 0xffff0000, v201
	v_lshlrev_b32_e32 v73, 16, v224
	v_and_b32_e32 v72, 0xffff0000, v224
	v_lshlrev_b32_e32 v83, 16, v225
	v_and_b32_e32 v82, 0xffff0000, v225
	v_lshlrev_b32_e32 v69, 16, v226
	v_and_b32_e32 v68, 0xffff0000, v226
	v_lshlrev_b32_e32 v85, 16, v227
	v_and_b32_e32 v84, 0xffff0000, v227
	v_pk_add_f32 v[70:71], v[74:75], v[72:73]
	v_mov_b32_e32 v74, v80
; DI void phaseC0_tile(const Params& p, int l, int t, char* smem) {
;     ...
; #pragma unroll 1
;       for (int c8 = 0; c8 < 4; ++c8) {
;         float a[8], bq[8];
;         unpack8(*(const uint4*)(y0 + 8 * c8), a);
;         unpack8(*(const uint4*)(y1 + 8 * c8), bq);
; #pragma unroll
;         for (int i = 0; i < 8; ++i) { float y = a[i] + bq[i]; s0 += y; s1 += y * y; }
;       }
;       s0 += __shfl_xor(s0, 1); s1 += __shfl_xor(s1, 1);
;       const float mean = s0 * (1.f / 64.f);
;       const float var = fmaxf(s1 * (1.f / 64.f) - mean * mean, 0.f);
;       const float rstd = rsqrtf(var + 64e-5f);
;       const float bon = p.bonus[(size_t)R * 8 + hd] + p.bonus[((size_t)NTOK + R) * 8 + hd];
;       const int s = R % TPB;
;       const int pos = s < CTXL ? s : s - CTXL, len = s < CTXL ? CTXL : SEQ;
;       const bool hp = pos > 0, hn = pos < len - 1;
	v_pk_mul_f32 v[72:73], v[70:71], v[70:71]
	v_add_f32_e32 v67, v67, v71
	v_add_f32_e32 v66, v66, v73
	v_add_f32_e32 v70, v70, v67
	v_add_f32_e32 v72, v72, v66
	v_pk_add_f32 v[66:67], v[76:77], v[82:83]
	s_nop 0
	v_add_f32_e32 v73, v67, v70
	v_pk_mul_f32 v[70:71], v[66:67], v[66:67]
	s_nop 0
	v_add_f32_e32 v67, v71, v72
	v_add_f32_e32 v71, v66, v73
	v_add_f32_e32 v70, v70, v67
	v_pk_add_f32 v[66:67], v[78:79], v[68:69]
	s_nop 0
	v_pk_mul_f32 v[68:69], v[66:67], v[66:67]
	v_add_f32_e32 v76, v67, v71
	v_add_f32_e32 v67, v69, v70
	v_pk_add_f32 v[70:71], v[80:81], v[84:85]
	v_mov_b32_e32 v75, v66
	v_pk_mul_f32 v[72:73], v[70:71], v[70:71]
	v_mov_b32_e32 v85, v76
	v_add_f32_e32 v68, v68, v67
	v_pk_add_f32 v[66:67], v[74:75], v[84:85]
	v_pk_mov_b32 v[72:73], v[72:73], v[80:81] op_sel:[1,0]
	v_mov_b32_e32 v69, v84
	v_pk_add_f32 v[68:69], v[72:73], v[68:69]
	v_pk_mul_f32 v[72:73], v[70:71], v[66:67]
	v_pk_add_f32 v[66:67], v[70:71], v[66:67]
	s_nop 0
	v_mov_b32_e32 v73, v67
	v_pk_add_f32 v[66:67], v[72:73], v[68:69]
	v_lshlrev_b32_e32 v75, 16, v202
	v_and_b32_e32 v74, 0xffff0000, v202
	v_lshlrev_b32_e32 v77, 16, v203
	v_and_b32_e32 v76, 0xffff0000, v203
	v_lshlrev_b32_e32 v79, 16, v204
	v_and_b32_e32 v78, 0xffff0000, v204
	v_lshlrev_b32_e32 v81, 16, v205
	v_and_b32_e32 v80, 0xffff0000, v205
	v_lshlrev_b32_e32 v73, 16, v234
	v_and_b32_e32 v72, 0xffff0000, v234
	v_lshlrev_b32_e32 v83, 16, v235
	v_and_b32_e32 v82, 0xffff0000, v235
	v_lshlrev_b32_e32 v69, 16, v236
	v_and_b32_e32 v68, 0xffff0000, v236
	v_lshlrev_b32_e32 v85, 16, v237
	v_and_b32_e32 v84, 0xffff0000, v237
	v_pk_add_f32 v[70:71], v[74:75], v[72:73]
	v_mov_b32_e32 v74, v80
	v_pk_mul_f32 v[72:73], v[70:71], v[70:71]
	v_add_f32_e32 v67, v67, v71
	v_add_f32_e32 v66, v66, v73
	v_add_f32_e32 v70, v70, v67
	v_add_f32_e32 v72, v72, v66
	v_pk_add_f32 v[66:67], v[76:77], v[82:83]
	s_nop 0
	v_add_f32_e32 v73, v67, v70
	v_pk_mul_f32 v[70:71], v[66:67], v[66:67]
	s_nop 0
	v_add_f32_e32 v67, v71, v72
	v_add_f32_e32 v71, v66, v73
	v_add_f32_e32 v70, v70, v67
	v_pk_add_f32 v[66:67], v[78:79], v[68:69]
	s_nop 0
	v_pk_mul_f32 v[68:69], v[66:67], v[66:67]
	v_add_f32_e32 v76, v67, v71
	v_add_f32_e32 v67, v69, v70
	v_pk_add_f32 v[70:71], v[80:81], v[84:85]
	v_mov_b32_e32 v75, v66
	v_pk_mul_f32 v[72:73], v[70:71], v[70:71]
	v_mov_b32_e32 v85, v76
	v_add_f32_e32 v68, v68, v67
	v_pk_add_f32 v[66:67], v[74:75], v[84:85]
	v_pk_mov_b32 v[72:73], v[72:73], v[80:81] op_sel:[1,0]
	v_mov_b32_e32 v69, v84
	v_pk_add_f32 v[68:69], v[72:73], v[68:69]
	v_pk_mul_f32 v[72:73], v[70:71], v[66:67]
	v_pk_add_f32 v[66:67], v[70:71], v[66:67]
	s_nop 0
	v_mov_b32_e32 v73, v67
	v_pk_add_f32 v[66:67], v[72:73], v[68:69]
	v_readlane_b32 s16, v254, 59
	v_lshlrev_b64 v[68:69], 5, v[64:65]
	v_readlane_b32 s20, v254, 63
	v_readlane_b32 s21, v255, 0
	v_mov_b32_e32 v99, v144
	s_mov_b32 s2, 0x110000
	v_lshl_add_u64 v[68:69], s[20:21], 0, v[68:69]
	v_lshl_add_u64 v[68:69], v[68:69], 0, v[98:99]
	v_add_co_u32_e32 v70, vcc, s2, v68
	v_xor_b32_e32 v65, 1, v217
	s_nop 0
	v_addc_co_u32_e32 v71, vcc, 0, v69, vcc
	global_load_dword v72, v[68:69], off
	s_nop 0
	global_load_dword v70, v[70:71], off
	v_and_b32_e32 v68, 64, v217
	s_mov_b32 s4, 0x78787879
	v_add_u32_e32 v68, 64, v68
	v_mul_hi_i32 v69, v64, s4
	v_cmp_lt_i32_e32 vcc, v65, v68
	v_lshrrev_b32_e32 v71, 31, v69
	v_ashrrev_i32_e32 v69, 11, v69
	v_cndmask_b32_e32 v65, v217, v65, vcc
	v_add_u32_e32 v68, v69, v71
	v_lshlrev_b32_e32 v65, 2, v65
	v_mul_i32_i24_e32 v71, 0x1100, v68
	ds_bpermute_b32 v69, v65, v67
	ds_bpermute_b32 v68, v65, v66
	v_sub_u32_e32 v64, v64, v71
	v_add_u32_e32 v65, 0xffffff00, v64
	v_cmp_gt_i32_e32 vcc, s33, v64
	s_mov_b32 s2, 0x3c800000
	v_lshl_add_u64 v[104:105], v[88:89], 0, v[100:101]
	v_cndmask_b32_e32 v71, v65, v64, vcc
	s_waitcnt lgkmcnt(0)
	v_pk_add_f32 v[64:65], v[66:67], v[68:69]
	v_cndmask_b32_e32 v73, v222, v223, vcc
	v_pk_mul_f32 v[106:107], v[64:65], s[2:3] op_sel_hi:[1,0]
	s_mov_b32 s2, 0x800000
	v_fma_f32 v64, -v107, v107, v106
	v_max_f32_e32 v64, 0, v64
	v_add_f32_e32 v64, 0x3a27c5ac, v64
	v_mul_f32_e32 v65, 0x4b800000, v64
	v_cmp_gt_f32_e32 vcc, s2, v64
	s_mov_b64 s[34:35], 0
	v_mov_b32_e32 v99, v145
	v_cndmask_b32_e32 v64, v64, v65, vcc
	v_rsq_f32_e32 v64, v64
	v_cmp_lt_i32_e64 s[6:7], 0, v71
	v_cmp_lt_i32_e64 s[8:9], v71, v73
	v_mov_b32_e32 v106, v107
	v_mul_f32_e32 v65, 0x45800000, v64
	v_cndmask_b32_e32 v108, v64, v65, vcc
	v_mov_b32_e32 v109, v108
	s_mov_b64 s[36:37], 0
	v_readlane_b32 s17, v254, 60
	v_readlane_b32 s18, v254, 61
	v_readlane_b32 s19, v254, 62
	v_readlane_b32 s22, v255, 1
	v_readlane_b32 s23, v255, 2
	v_readlane_b32 s24, v255, 3
	v_readlane_b32 s25, v255, 4
	v_readlane_b32 s26, v255, 5
	v_readlane_b32 s27, v255, 6
	v_readlane_b32 s28, v255, 7
	v_readlane_b32 s29, v255, 8
	v_readlane_b32 s30, v255, 9
	v_readlane_b32 s31, v255, 10
	s_waitcnt vmcnt(0)
	v_add_f32_e32 v110, v72, v70
	v_mov_b32_e32 v111, v110
	s_branch .LBB0_352

; DI bool swz_tile(int i, int NC, int& rt, int& ct) {
;   const int G = gridDim.x;
;   if ((G & 7) == 0) {
;     const int x = blockIdx.x & 7, j = blockIdx.x >> 3, per = G >> 3;
;     const int T8 = NROWT * NC / 8;
;     const int ul = i * per + j;
;     if (ul >= T8) return false;
;     const int u = x * T8 + ul;
;     const int band = u / (8 * NC), rem = u % (8 * NC);
;     ct = rem >> 3; rt = band * 8 + (rem & 7);
;     return true;
;   }
.LBB0_376:
	s_mul_i32 s4, s97, s96
	v_readlane_b32 s0, v254, 18
	s_add_i32 s4, s4, s0
	v_readlane_b32 s0, v253, 2
	s_cmp_ge_i32 s0, 29
	s_cselect_b32 s0, 16, 0
	s_sub_i32 s0, 0x10f, s0
	s_cmp_gt_i32 s4, s0
	s_mov_b64 s[0:1], 0
	s_cbranch_scc1 .LBB0_378
	v_readlane_b32 s0, v254, 26
	v_readlane_b32 s1, v253, 2
	s_cmp_ge_i32 s1, 29
	s_cbranch_scc0 .Lctxsw3_a
	v_readlane_b32 s0, v254, 36
	s_and_b32 s0, s0, 7
	s_lshl_b32 s0, s0, 8

; DI bool swz_tile(int i, int NC, int& rt, int& ct) {
;     ...
;     if (ul >= T8) return false;
;     const int u = x * T8 + ul;
;     const int band = u / (8 * NC), rem = u % (8 * NC);
;     ct = rem >> 3; rt = band * 8 + (rem & 7);
;     return true;
.Lctxsw3_b:
	s_mov_b64 s[0:1], -1
.LBB0_378:
	s_mov_b32 s80, s2
	s_mov_b32 s78, s6
	s_andn2_b64 vcc, exec, s[0:1]
	s_mov_b64 s[0:1], -1
	s_cbranch_vccz .LBB0_209

; DI u16 f2bf(float f) { unsigned u = __float_as_uint(f); u += 0x7fffu + ((u >> 16) & 1u); return (u16)(u >> 16); }
; DI void s5_job(const Params& p, int l, int job, char* smem) {
;     ...
;   bf16x8 cf[4];
; #pragma unroll
;   for (int ks = 0; ks < 4; ++ks)
; #pragma unroll
;     for (int j = 0; j < 8; ++j) {
;       int k = 32 * ks + 8 * quad + j, n = k >> 1;
;       size_t idx = ((size_t)(l * 32 + g) * 16 + col) * 64 + n;
;       float v = (k & 1) == 0 ? p.ssm_c_re[idx] : -p.ssm_c_im[idx];
;       cf[ks][j] = (short)f2bf(v);
;     }
;   const float dsk = p.ssm_d[l * 512 + g * 16 + col];
; DI void phaseB(const Params& p, int l, char* smem) {
;     ...
;   if (slot == 0) {
;     const int job = fetch_job(p.ctr + l, &s_job);
;     if (job < NJ_RWKV) { __builtin_amdgcn_s_setprio(3); rwkv_job(p, l, job, smem); __builtin_amdgcn_s_setprio(0); }
;   } else {
;     const int job = fetch_job(p.ctr + 4 + l, &s_job);
;     if (job < NJ_S5) { __builtin_amdgcn_s_setprio(2); s5_job(p, l, job, smem); __builtin_amdgcn_s_setprio(0); }
.LBB0_391:
	s_or_b64 exec, exec, s[0:1]
	s_waitcnt lgkmcnt(0)
	s_barrier
	ds_read_b32 v0, v218
	s_mov_b64 s[4:5], 0
	s_mov_b64 s[0:1], 0
	s_waitcnt lgkmcnt(0)
	v_cmp_lt_i32_e32 vcc, 63, v0
	v_readfirstlane_b32 s2, v0
	s_cbranch_vccnz .LBB0_531
	s_setprio 2
	s_waitcnt vmcnt(4)
	v_mov_b32_e32 v38, v216
	s_lshl_b32 s0, s2, 2
	s_and_b32 s0, s0, 28
	v_ashrrev_i32_e32 v39, 6, v38
	s_waitcnt vmcnt(2)
	v_add_u32_e32 v56, s0, v39
	v_readlane_b32 s8, v255, 44
	v_and_b32_e32 v58, 15, v38
	v_readlane_b32 s12, v253, 38
	v_lshl_add_u32 v0, s8, 5, v56
	v_ashrrev_i32_e32 v1, 31, v0
	v_lshlrev_b64 v[0:1], 10, v[0:1]
	v_lshl_or_b32 v2, v58, 6, v0
	v_mov_b32_e32 v3, v1
	v_lshlrev_b64 v[6:7], 2, v[2:3]
	v_readlane_b32 s16, v253, 42
	v_readlane_b32 s17, v253, 43
	v_and_b32_e32 v16, 48, v38
	v_mov_b32_e32 v17, v144
	v_lshl_add_u64 v[2:3], s[16:17], 0, v[6:7]
	v_lshl_add_u64 v[14:15], v[2:3], 0, v[16:17]
	global_load_dwordx4 v[2:5], v[14:15], off
	v_readlane_b32 s14, v253, 40
	v_readlane_b32 s15, v253, 41
	v_readlane_b32 s18, v253, 44
	v_readlane_b32 s19, v253, 45
	v_lshl_add_u64 v[6:7], s[14:15], 0, v[6:7]
	v_lshl_add_u64 v[34:35], v[6:7], 0, v[16:17]
	global_load_dwordx4 v[6:9], v[34:35], off
	global_load_dwordx4 v[10:13], v[14:15], off offset:64
	global_load_dwordx4 v[18:21], v[34:35], off offset:64
	global_load_dwordx4 v[22:25], v[14:15], off offset:128
	global_load_dwordx4 v[26:29], v[34:35], off offset:128
	global_load_dwordx4 v[30:33], v[14:15], off offset:192
	v_lshlrev_b32_e32 v14, 4, v56
	global_load_dwordx4 v[34:37], v[34:35], off offset:192
	s_ashr_i32 s0, s2, 3
	s_mul_i32 s2, s0, 0x1fe0000
	s_mul_hi_i32 s1, s0, 0x1fe0000
	s_mul_hi_i32 s4, s0, 0x440000
	s_mul_i32 s5, s0, 0x440000
	s_add_u32 s0, s60, s2
	s_movk_i32 s2, 0x3200
	s_addc_u32 s1, s61, s1
	v_and_b32_e32 v60, 63, v38
	v_bfe_u32 v38, v38, 4, 2
	v_mul_lo_u32 v39, v39, s2
	s_add_u32 s6, s66, s5
	v_ashrrev_i32_e32 v15, 31, v14
	v_readlane_b32 s20, v253, 46
	v_readlane_b32 s21, v253, 47
	v_readlane_b32 s22, v253, 48
	v_readlane_b32 s23, v253, 49
	v_readlane_b32 s24, v253, 50
	v_readlane_b32 s25, v253, 51
	v_readlane_b32 s26, v253, 52
	v_readlane_b32 s27, v253, 53
	s_addc_u32 s7, s67, s4
	v_ashrrev_i32_e32 v57, 31, v56
	v_lshlrev_b64 v[62:63], 6, v[56:57]
	v_readlane_b32 s9, v255, 45
	v_readlane_b32 s13, v253, 39
	v_lshl_or_b32 v0, v38, 3, v0
	s_lshl_b32 s2, s8, 1
	v_lshlrev_b32_e32 v61, 2, v38
	v_lshl_or_b32 v183, v60, 2, v39
	v_mov_b32_e32 v59, v144
	s_mov_b64 s[34:35], -1
	s_movk_i32 s4, 0xf0
	s_waitcnt vmcnt(7)
	v_xor_b32_e32 v2, 0x80000000, v2
	v_bfe_u32 v55, v2, 16, 1
	v_xor_b32_e32 v3, 0x80000000, v3
	v_add3_u32 v55, v2, v55, s38
	v_lshl_add_u32 v2, s8, 9, v14
	v_bfe_u32 v54, v3, 16, 1
	v_or_b32_e32 v2, v2, v58
	v_add3_u32 v54, v3, v54, s38
	v_ashrrev_i32_e32 v3, 31, v2
	v_lshl_add_u64 v[2:3], v[2:3], 2, s[18:19]
	global_load_dword v182, v[2:3], off
	s_waitcnt vmcnt(7)
	v_bfe_u32 v43, v6, 16, 1
	s_waitcnt vmcnt(6)
	v_xor_b32_e32 v13, 0x80000000, v13
	v_xor_b32_e32 v4, 0x80000000, v4
	v_xor_b32_e32 v5, 0x80000000, v5
	v_bfe_u32 v40, v9, 16, 1
	v_bfe_u32 v41, v8, 16, 1
	v_bfe_u32 v42, v7, 16, 1
	v_xor_b32_e32 v10, 0x80000000, v10
	v_xor_b32_e32 v11, 0x80000000, v11
	v_xor_b32_e32 v12, 0x80000000, v12
	s_waitcnt vmcnt(5)
	v_bfe_u32 v44, v21, 16, 1
	v_bfe_u32 v45, v20, 16, 1
	v_bfe_u32 v46, v19, 16, 1
	s_waitcnt vmcnt(4)
	v_xor_b32_e32 v22, 0x80000000, v22
	v_xor_b32_e32 v23, 0x80000000, v23
	v_xor_b32_e32 v24, 0x80000000, v24
	v_add3_u32 v43, v6, v43, s38
	v_bfe_u32 v6, v13, 16, 1
	v_bfe_u32 v47, v18, 16, 1
	v_xor_b32_e32 v25, 0x80000000, v25
	s_waitcnt vmcnt(3)
	v_bfe_u32 v49, v28, 16, 1
	v_bfe_u32 v52, v5, 16, 1
	v_bfe_u32 v53, v4, 16, 1
	v_add3_u32 v42, v7, v42, s38
	v_add3_u32 v8, v8, v41, s38
	v_add3_u32 v9, v9, v40, s38
	v_bfe_u32 v7, v12, 16, 1
	v_bfe_u32 v40, v11, 16, 1
	v_bfe_u32 v41, v10, 16, 1
	v_add3_u32 v46, v19, v46, s38
	v_add3_u32 v45, v20, v45, s38
	v_add3_u32 v44, v21, v44, s38
	v_bfe_u32 v19, v24, 16, 1
	v_bfe_u32 v20, v23, 16, 1
	v_bfe_u32 v21, v22, 16, 1
	v_add3_u32 v13, v13, v6, s38
	s_waitcnt vmcnt(2)
; DI u16 f2bf(float f) { unsigned u = __float_as_uint(f); u += 0x7fffu + ((u >> 16) & 1u); return (u16)(u >> 16); }
; DI void s5_job(const Params& p, int l, int job, char* smem) {
;     ...
;   bf16x8 cf[4];
; #pragma unroll
;   for (int ks = 0; ks < 4; ++ks)
; #pragma unroll
;     for (int j = 0; j < 8; ++j) {
;       int k = 32 * ks + 8 * quad + j, n = k >> 1;
;       size_t idx = ((size_t)(l * 32 + g) * 16 + col) * 64 + n;
;       float v = (k & 1) == 0 ? p.ssm_c_re[idx] : -p.ssm_c_im[idx];
;       cf[ks][j] = (short)f2bf(v);
;     }
;   const float dsk = p.ssm_d[l * 512 + g * 16 + col];
	v_xor_b32_e32 v6, 0x80000000, v32
	v_bfe_u32 v48, v29, 16, 1
	v_add3_u32 v47, v18, v47, s38
	v_bfe_u32 v18, v25, 16, 1
	v_add3_u32 v53, v4, v53, s38
	v_add3_u32 v52, v5, v52, s38
	v_add3_u32 v10, v10, v41, s38
	v_add3_u32 v11, v11, v40, s38
	v_add3_u32 v12, v12, v7, s38
	v_add3_u32 v40, v22, v21, s38
	v_add3_u32 v41, v23, v20, s38
	v_add3_u32 v28, v28, v49, s38
	v_add3_u32 v49, v24, v19, s38
	v_xor_b32_e32 v4, 0x80000000, v30
	v_xor_b32_e32 v5, 0x80000000, v31
	v_xor_b32_e32 v7, 0x80000000, v33
	s_waitcnt vmcnt(1)
	v_bfe_u32 v2, v37, 16, 1
	v_bfe_u32 v3, v6, 16, 1
	v_bfe_u32 v19, v36, 16, 1
	v_bfe_u32 v21, v35, 16, 1
	v_bfe_u32 v23, v34, 16, 1
	v_add3_u32 v29, v29, v48, s38
	v_add3_u32 v48, v25, v18, s38
	v_bfe_u32 v18, v7, 16, 1
	v_bfe_u32 v20, v5, 16, 1
	v_bfe_u32 v22, v4, 16, 1
	v_add3_u32 v30, v34, v23, s38
	v_add3_u32 v32, v35, v21, s38
	v_add3_u32 v34, v36, v19, s38
	v_add3_u32 v35, v6, v3, s38
	v_add3_u32 v36, v37, v2, s38
	v_lshlrev_b64 v[2:3], 1, v[14:15]
	v_lshl_add_u32 v6, v38, 11, v39
	v_add3_u32 v31, v4, v22, s38
	v_add3_u32 v33, v5, v20, s38
	v_add3_u32 v37, v7, v18, s38
	v_lshl_add_u64 v[4:5], s[0:1], 0, v[2:3]
	s_mov_b64 s[0:1], 0x1a00
	v_lshl_add_u64 v[2:3], s[6:7], 0, v[2:3]
	v_lshl_or_b32 v57, v58, 2, v6
	v_lshlrev_b32_e32 v6, 1, v58
	v_mov_b32_e32 v7, v144
	v_readlane_b32 s16, v253, 22
	v_lshl_add_u64 v[4:5], v[4:5], 0, s[0:1]
	v_lshl_add_u64 v[66:67], v[2:3], 0, v[6:7]
	v_lshlrev_b32_e32 v2, 4, v58
	v_mov_b32_e32 v3, v144
	v_readlane_b32 s17, v253, 23
	v_readlane_b32 s18, v253, 24
	v_readlane_b32 s19, v253, 25
	v_readlane_b32 s20, v253, 26
	v_readlane_b32 s21, v253, 27
	v_readlane_b32 s22, v253, 28
	v_readlane_b32 s23, v253, 29
	v_lshl_add_u64 v[64:65], v[4:5], 0, v[6:7]
	v_lshl_add_u64 v[68:69], v[4:5], 0, v[16:17]
	v_lshl_add_u64 v[18:19], v[0:1], 0, v[2:3]
	v_or_b32_e32 v4, 0x100, v2
	v_mov_b32_e32 v5, v144
	v_readlane_b32 s8, v253, 38
	v_lshl_add_u64 v[20:21], v[0:1], 0, v[4:5]
	v_or_b32_e32 v4, 0x200, v2
	v_lshlrev_b64 v[18:19], 2, v[18:19]
	v_readlane_b32 s30, v253, 36
	v_readlane_b32 s31, v253, 37
	v_readlane_b32 s9, v253, 39
	v_lshl_add_u64 v[22:23], v[0:1], 0, v[4:5]
	v_or_b32_e32 v2, 0x300, v2
	v_lshl_add_u64 v[70:71], s[30:31], 0, v[18:19]
	v_lshl_add_u64 v[72:73], s[8:9], 0, v[18:19]
	v_lshlrev_b64 v[18:19], 2, v[20:21]
	v_bfe_u32 v50, v27, 16, 1
	v_bfe_u32 v51, v26, 16, 1
	s_movk_i32 s0, 0x110
	v_lshl_add_u64 v[24:25], v[0:1], 0, v[2:3]
	v_lshl_add_u64 v[74:75], s[30:31], 0, v[18:19]
	v_lshl_add_u64 v[76:77], s[8:9], 0, v[18:19]
	v_lshlrev_b64 v[18:19], 2, v[22:23]
	v_add3_u32 v26, v26, v51, s38
	v_add3_u32 v27, v27, v50, s38
	v_mad_u32_u24 v38, v58, s0, v39
	v_readlane_b32 s14, v253, 44
	v_readlane_b32 s15, v253, 45
	v_lshl_add_u64 v[78:79], s[30:31], 0, v[18:19]
	v_lshl_add_u64 v[80:81], s[8:9], 0, v[18:19]
	v_lshlrev_b64 v[18:19], 2, v[24:25]
	v_cmp_gt_u32_e64 s[6:7], 32, v60
	v_perm_b32 v3, v52, v9, s87
	v_perm_b32 v2, v53, v8, s87
	v_perm_b32 v1, v54, v42, s87
	v_perm_b32 v0, v55, v43, s87
	v_perm_b32 v7, v13, v44, s87
	v_perm_b32 v6, v12, v45, s87
	v_perm_b32 v5, v11, v46, s87
	v_perm_b32 v4, v10, v47, s87
	v_perm_b32 v11, v48, v29, s87
	v_perm_b32 v10, v49, v28, s87
	v_perm_b32 v9, v41, v27, s87
	v_perm_b32 v8, v40, v26, s87
	v_perm_b32 v15, v37, v36, s87
	v_perm_b32 v14, v35, v34, s87
	v_perm_b32 v13, v33, v32, s87
	v_perm_b32 v12, v31, v30, s87
	v_lshl_add_u64 v[82:83], s[30:31], 0, v[18:19]
	v_lshl_add_u64 v[84:85], s[8:9], 0, v[18:19]
	s_mov_b32 s0, 0
	s_mov_b64 s[14:15], 0
	v_add_u32_e32 v184, v38, v16
	v_readlane_b32 s24, v253, 30
	v_readlane_b32 s25, v253, 31
	v_readlane_b32 s26, v253, 32
	v_readlane_b32 s27, v253, 33
	v_readlane_b32 s28, v253, 34
	v_readlane_b32 s29, v253, 35
	v_readlane_b32 s10, v253, 40
	v_readlane_b32 s11, v253, 41
	v_readlane_b32 s12, v253, 42
	v_readlane_b32 s13, v253, 43
	v_readlane_b32 s16, v253, 46
	v_readlane_b32 s17, v253, 47
	v_readlane_b32 s18, v253, 48
	v_readlane_b32 s19, v253, 49
	v_readlane_b32 s20, v253, 50
	v_readlane_b32 s21, v253, 51
	v_readlane_b32 s22, v253, 52
	v_readlane_b32 s23, v253, 53
	s_branch .LBB0_394

; DI u16 f2bf(float f) { unsigned u = __float_as_uint(f); u += 0x7fffu + ((u >> 16) & 1u); return (u16)(u >> 16); }
; DI void s5_job(const Params& p, int l, int job, char* smem) {
;     ...
;       float mag = expf(lr * dt);
;       abr = mag * cosf(li * dt); abi = mag * sinf(li * dt);
;     }
;     bf16x8 bfr[8];
; #pragma unroll
;     for (int q4 = 0; q4 < 4; ++q4) {
;       const int n = 16 * q4 + col;
;       size_t ia = ((size_t)(l * 2 + d) * 32 + g) * 64 + n;
;       float lr = fminf(p.ssm_a_re[ia], -1e-4f), li = p.ssm_a_im[ia];
;       float mag = expf(lr * dt);
;       float ar = mag * cosf(li * dt), ai = mag * sinf(li * dt);
;       float nr = ar - 1.f, ni = ai;
;       float den = lr * lr + li * li;
;       float cr = (nr * lr + ni * li) / den, ci = (ni * lr - nr * li) / den;
; #pragma unroll
;       for (int j = 0; j < 8; ++j) {
;         float vr = 0.f, vi = 0.f;
;         if (quad < 2) {
;           size_t ib = ((size_t)(l * 32 + g) * 64 + n) * 16 + 8 * quad + j;
;           float br = p.ssm_b_re[ib], bi = p.ssm_b_im[ib];
;           vr = cr * br - ci * bi; vi = cr * bi + ci * br;
;         }
;         bfr[q4][j] = (short)f2bf(vr);
;         bfr[4 + q4][j] = (short)f2bf(vi);
;       }
;     }
;     float xr = 0.f, xi = 0.f;
;     bf16x8 ua_next = {0, 0, 0, 0, 0, 0, 0, 0};
;     if (quad < 2) ua_next = *(const bf16x8*)(Pb + (size_t)((d == 0 ? 0 : CTXL - 16) + col) * PW + 8 * quad);
.LBB0_500:
	s_or_b64 exec, exec, s[0:1]
	v_mul_f32_e32 v17, v192, v192
	v_fmamk_f32 v19, v17, 0xb94c1982, v219
	v_fmaak_f32 v19, v17, v19, 0xbe2aaa9d
	v_mul_f32_e32 v19, v17, v19
	v_fmac_f32_e32 v192, v192, v19
	v_fmamk_f32 v19, v17, 0x37d75334, v220
	v_fmaak_f32 v19, v17, v19, 0x3d2aabf7
	v_fmaak_f32 v19, v17, v19, 0xbf000004
	v_fma_f32 v17, v17, v19, 1.0
	v_and_b32_e32 v19, 1, v191
	v_cmp_eq_u32_e32 vcc, 0, v19
	v_lshlrev_b32_e32 v19, 30, v191
	v_and_b32_e32 v19, 0x80000000, v19
	v_xor_b32_e32 v20, v190, v187
	v_xor_b32_e32 v19, v20, v19
	v_max_f32_e32 v20, v189, v189
	v_min_f32_e32 v20, 0xb8d1b717, v20
	v_mul_f32_e32 v20, v188, v20
	v_mul_f32_e32 v22, 0x3fb8aa3b, v20
	s_mov_b32 s0, 0x3fb8aa3b
	v_fma_f32 v25, v20, s0, -v22
	v_rndne_f32_e32 v27, v22
	v_fmac_f32_e32 v25, 0x32a5705f, v20
	v_sub_f32_e32 v22, v22, v27
	v_add_f32_e32 v22, v22, v25
	v_exp_f32_e32 v22, v22
	v_cvt_i32_f32_e32 v25, v27
	s_movk_i32 s0, 0x1f8
	v_cndmask_b32_e32 v17, v17, v192, vcc
	v_cmp_class_f32_e64 vcc, v187, s0
	s_mov_b32 s0, 0xc2ce8ed0
	v_xor_b32_e32 v17, v19, v17
	v_ldexp_f32 v19, v22, v25
	v_cmp_ngt_f32_e64 s[0:1], s0, v20
	v_cndmask_b32_e32 v17, v232, v17, vcc
	v_mov_b32_e32 v94, 0
	v_cndmask_b32_e64 v19, 0, v19, s[0:1]
	s_mov_b32 s0, 0x42b17218
	v_cmp_nlt_f32_e64 s[0:1], s0, v20
	v_bfe_u32 v20, v181, 16, 1
	v_add3_u32 v28, v181, v20, s38
	v_cndmask_b32_e64 v19, v231, v19, s[0:1]
	v_mul_f32_e32 v86, v19, v17
	v_bfe_u32 v17, v177, 16, 1
	v_add3_u32 v30, v177, v17, s38
	v_bfe_u32 v17, v174, 16, 1
	v_add3_u32 v46, v174, v17, s38
	v_bfe_u32 v17, v173, 16, 1
	v_add3_u32 v33, v173, v17, s38
	v_bfe_u32 v17, v168, 16, 1
	v_add3_u32 v49, v168, v17, s38
	v_bfe_u32 v17, v171, 16, 1
	v_add3_u32 v35, v171, v17, s38
	v_bfe_u32 v17, v166, 16, 1
	v_add3_u32 v51, v166, v17, s38
	v_bfe_u32 v17, v165, 16, 1
	v_add3_u32 v36, v165, v17, s38
	v_bfe_u32 v17, v160, 16, 1
	v_add3_u32 v91, v160, v17, s38
	v_bfe_u32 v17, v163, 16, 1
	v_add3_u32 v38, v163, v17, s38
	v_bfe_u32 v17, v158, 16, 1
	v_add3_u32 v93, v158, v17, s38
	v_bfe_u32 v17, v157, 16, 1
	v_add3_u32 v41, v157, v17, s38
	v_bfe_u32 v17, v150, 16, 1
	v_add3_u32 v96, v150, v17, s38
	v_bfe_u32 v17, v155, 16, 1
	v_add3_u32 v43, v155, v17, s38
	v_bfe_u32 v17, v152, 16, 1
	v_add3_u32 v99, v152, v17, s38
	v_bfe_u32 v17, v149, 16, 1
	v_add3_u32 v25, v149, v17, s38
	v_bfe_u32 v17, v140, 16, 1
	v_add3_u32 v101, v140, v17, s38
	v_bfe_u32 v17, v143, 16, 1
	v_add3_u32 v27, v143, v17, s38
	v_bfe_u32 v17, v138, 16, 1
	v_add3_u32 v102, v138, v17, s38
	v_bfe_u32 v17, v137, 16, 1
	v_add3_u32 v104, v137, v17, s38
	v_bfe_u32 v17, v132, 16, 1
	v_add3_u32 v107, v132, v17, s38
	v_bfe_u32 v17, v135, 16, 1
	v_add3_u32 v109, v135, v17, s38
	v_bfe_u32 v17, v130, 16, 1
	v_add3_u32 v110, v130, v17, s38
	v_bfe_u32 v17, v129, 16, 1
	v_add3_u32 v112, v129, v17, s38
	v_bfe_u32 v17, v124, 16, 1
	v_add3_u32 v115, v124, v17, s38
	v_bfe_u32 v17, v127, 16, 1
	v_add3_u32 v117, v127, v17, s38
	v_bfe_u32 v17, v122, 16, 1
	v_add3_u32 v118, v122, v17, s38
	v_bfe_u32 v17, v121, 16, 1
	v_add3_u32 v120, v121, v17, s38
	v_bfe_u32 v17, v114, 16, 1
	v_add3_u32 v114, v114, v17, s38
	v_bfe_u32 v17, v119, 16, 1
	v_add3_u32 v119, v119, v17, s38
	v_bfe_u32 v17, v116, 16, 1
	v_bfe_u32 v20, v178, 16, 1
	v_add3_u32 v116, v116, v17, s38
	v_bfe_u32 v17, v113, 16, 1
	v_add3_u32 v44, v178, v20, s38
	v_add3_u32 v20, v113, v17, s38
	v_bfe_u32 v17, v108, 16, 1
	v_add3_u32 v108, v108, v17, s38
	v_bfe_u32 v17, v111, 16, 1
	v_add3_u32 v22, v111, v17, s38
	v_bfe_u32 v17, v106, 16, 1
	v_add3_u32 v106, v106, v17, s38
	v_bfe_u32 v17, v105, 16, 1
	v_add3_u32 v105, v105, v17, s38
	v_bfe_u32 v17, v100, 16, 1
	v_add3_u32 v100, v100, v17, s38
	v_bfe_u32 v17, v103, 16, 1
	v_add3_u32 v103, v103, v17, s38
	v_bfe_u32 v17, v98, 16, 1
	v_add3_u32 v98, v98, v17, s38
	v_bfe_u32 v17, v97, 16, 1
	v_add3_u32 v97, v97, v17, s38
	v_bfe_u32 v17, v92, 16, 1
	v_add3_u32 v92, v92, v17, s38
	v_bfe_u32 v17, v95, 16, 1
	v_add3_u32 v95, v95, v17, s38
	v_bfe_u32 v17, v90, 16, 1
	v_add3_u32 v90, v90, v17, s38
	v_bfe_u32 v17, v89, 16, 1
	v_add3_u32 v89, v89, v17, s38
	v_bfe_u32 v17, v48, 16, 1
	v_add3_u32 v48, v48, v17, s38
	v_bfe_u32 v17, v87, 16, 1
	v_add3_u32 v87, v87, v17, s38
	v_bfe_u32 v17, v50, 16, 1
	v_add3_u32 v50, v50, v17, s38
	v_bfe_u32 v17, v47, 16, 1
	v_add3_u32 v17, v47, v17, s38
	v_bfe_u32 v47, v42, 16, 1
	v_add3_u32 v42, v42, v47, s38
	v_bfe_u32 v47, v45, 16, 1
	v_add3_u32 v45, v45, v47, s38
	v_bfe_u32 v47, v40, 16, 1
	v_add3_u32 v40, v40, v47, s38
	v_bfe_u32 v47, v39, 16, 1
	v_add3_u32 v39, v39, v47, s38
	v_bfe_u32 v47, v34, 16, 1
	v_add3_u32 v34, v34, v47, s38
	v_bfe_u32 v47, v37, 16, 1
	v_add3_u32 v37, v37, v47, s38
	v_bfe_u32 v47, v32, 16, 1
	v_add3_u32 v32, v32, v47, s38
	v_bfe_u32 v47, v31, 16, 1
	v_add3_u32 v31, v31, v47, s38
	v_bfe_u32 v47, v26, 16, 1
	v_add3_u32 v47, v26, v47, s38
	v_bfe_u32 v26, v29, 16, 1
	v_add3_u32 v26, v29, v26, s38
	v_bfe_u32 v29, v24, 16, 1
	v_add3_u32 v111, v24, v29, s38
	v_bfe_u32 v24, v23, 16, 1
	v_add3_u32 v23, v23, v24, s38
	v_bfe_u32 v24, v16, 16, 1
	v_add3_u32 v113, v16, v24, s38
	v_bfe_u32 v16, v21, 16, 1
	v_add3_u32 v16, v21, v16, s38
	v_bfe_u32 v21, v18, 16, 1
	v_add3_u32 v121, v18, v21, s38
	v_mul_f32_e32 v18, v186, v186
	v_fmamk_f32 v21, v18, 0xb94c1982, v219
	v_fmaak_f32 v21, v18, v21, 0xbe2aaa9d
	v_mul_f32_e32 v21, v18, v21
	v_fmac_f32_e32 v186, v186, v21
	v_fmamk_f32 v21, v18, 0x37d75334, v220
	v_fmaak_f32 v21, v18, v21, 0x3d2aabf7
	v_fmaak_f32 v21, v18, v21, 0xbf000004
	v_fma_f32 v18, v18, v21, 1.0
	v_and_b32_e32 v21, 1, v185
	v_cmp_eq_u32_e64 s[0:1], 0, v21
	v_lshlrev_b32_e32 v21, 30, v185
	s_xor_b64 s[10:11], s[14:15], -1
	v_cndmask_b32_e64 v18, -v186, v18, s[0:1]
	s_brev_b32 s0, 1
	v_bitop3_b32 v18, v21, v18, s0 bitop3:0x6c
	v_cndmask_b32_e32 v18, v232, v18, vcc
	v_mul_f32_e32 v88, v19, v18
	s_xor_b64 s[8:9], s[34:35], -1
	s_mov_b32 s34, 1
	s_mov_b32 s35, 0
	v_perm_b32 v19, v17, v45, s87
	v_perm_b32 v18, v39, v37, s87
	v_perm_b32 v17, v31, v26, s87
	v_perm_b32 v16, v23, v16, s87
	v_perm_b32 v23, v20, v22, s87
	v_perm_b32 v22, v105, v103, s87
	v_perm_b32 v21, v97, v95, s87
	v_perm_b32 v20, v89, v87, s87
	v_perm_b32 v27, v25, v27, s87
	v_perm_b32 v26, v104, v109, s87
	v_perm_b32 v25, v112, v117, s87
	v_perm_b32 v24, v120, v119, s87
	v_perm_b32 v31, v28, v30, s87
	v_perm_b32 v30, v33, v35, s87
	v_perm_b32 v29, v36, v38, s87
	v_perm_b32 v28, v41, v43, s87
	v_perm_b32 v35, v42, v40, s87
	v_perm_b32 v34, v34, v32, s87
	v_perm_b32 v33, v47, v111, s87
	v_perm_b32 v32, v113, v121, s87
	v_perm_b32 v39, v108, v106, s87
	v_perm_b32 v38, v100, v98, s87
	v_perm_b32 v37, v92, v90, s87
	v_perm_b32 v36, v48, v50, s87
	v_perm_b32 v43, v101, v102, s87
	v_perm_b32 v42, v107, v110, s87
	v_perm_b32 v41, v115, v118, s87
	v_perm_b32 v40, v114, v116, s87
	v_perm_b32 v47, v44, v46, s87
	v_perm_b32 v46, v49, v51, s87
	v_perm_b32 v45, v91, v93, s87
	v_perm_b32 v44, v96, v99, s87
	v_mov_b32_e32 v89, v88
	v_mov_b32_e32 v87, v86
	s_mov_b32 s36, 0
	v_mov_b32_e32 v95, v94
	s_waitcnt vmcnt(0)
	s_branch .LBB0_502
; DI void s5_job(const Params& p, int l, int job, char* smem) {
;     ...
;     for (int c = 0; c < TPB / 16; ++c) {
;       int tlo;
;       if (d == 0) tlo = 16 * c;
;       else tlo = c < 16 ? (CTXL - 16 - 16 * c) : (CTXL + SEQ - 16 - 16 * (c - 16));
;       bf16x8 ua = ua_next;
.LBB0_501:
	s_add_i32 s35, s35, 16
	s_add_i32 s34, s34, 1
	s_add_i32 s36, s36, 1
	s_waitcnt vmcnt(4)
	v_mov_b64_e32 v[54:55], v[50:51]
	s_cmpk_eq_i32 s35, 0x1100
	v_mov_b64_e32 v[52:53], v[48:49]
	s_cbranch_scc1 .LBB0_393

; DI void s5_job(const Params& p, int l, int job, char* smem) {
;     ...
;       bf16x8 ua = ua_next;
;       {
;         const int cn = c + 1 < TPB / 16 ? c + 1 : c;
;         int tln;
;         if (d == 0) tln = 16 * cn;
;         else tln = cn < 16 ? (CTXL - 16 - 16 * cn) : (CTXL + SEQ - 16 - 16 * (cn - 16));
;         if (quad < 2) ua_next = *(const bf16x8*)(Pb + (size_t)(tln + col) * PW + 8 * quad);
;       }
.LBB0_506:
	v_mov_b64_e32 v[48:49], v[52:53]
	v_mov_b64_e32 v[50:51], v[54:55]
	s_and_saveexec_b64 s[0:1], s[6:7]
	s_cbranch_execz .LBB0_508

; DI void s5_job(const Params& p, int l, int job, char* smem) {
;     ...
;       u16 pu[4] = {0, 0, 0, 0}, psb[4] = {0, 0, 0, 0};
;       if (pass == 1) {
; #pragma unroll
;         for (int q = 0; q < 4; ++q) { pu[q] = Pb[(size_t)(tlo + quad * 4 + q) * PW + col]; psb[q] = Sb[(size_t)(tlo + quad * 4 + q) * 512 + col]; }
;       }
.LBB0_508:
	s_or_b64 exec, exec, s[0:1]
	v_add_u32_e32 v98, s4, v61
	s_mov_b32 s1, 1
	s_andn2_b64 vcc, exec, s[14:15]
	v_ashrrev_i32_e32 v99, 31, v98
	v_add_u32_e32 v96, 1, v98
	v_add_u32_e32 v92, 2, v98
	v_add_u32_e32 v90, 3, v98
	s_cbranch_vccnz .LBB0_512
	v_ashrrev_i32_e32 v97, 31, v96
	v_lshlrev_b64 v[102:103], 10, v[98:99]
	v_lshlrev_b64 v[106:107], 10, v[96:97]
	v_ashrrev_i32_e32 v93, 31, v92
	v_ashrrev_i32_e32 v91, 31, v90
	v_mad_i64_i32 v[100:101], s[0:1], v98, s81, v[64:65]
	v_lshl_add_u64 v[102:103], v[66:67], 0, v[102:103]
	v_mad_i64_i32 v[104:105], s[0:1], v96, s81, v[64:65]
	v_lshl_add_u64 v[106:107], v[66:67], 0, v[106:107]
	v_lshlrev_b64 v[110:111], 10, v[92:93]
	v_lshlrev_b64 v[114:115], 10, v[90:91]
	v_mad_i64_i32 v[108:109], s[0:1], v92, s81, v[64:65]
	v_lshl_add_u64 v[110:111], v[66:67], 0, v[110:111]
	v_mad_i64_i32 v[112:113], s[0:1], v90, s81, v[64:65]
	v_lshl_add_u64 v[114:115], v[66:67], 0, v[114:115]
	global_load_ushort v234, v[100:101], off
	global_load_ushort v235, v[104:105], off
	s_nop 0
	global_load_ushort v236, v[112:113], off
	global_load_ushort v237, v[108:109], off
	s_nop 0
	global_load_ushort v238, v[102:103], off
	s_nop 0
	global_load_ushort v239, v[106:107], off
	s_nop 0
	global_load_ushort v240, v[114:115], off
	global_load_ushort v241, v[110:111], off
	s_mov_b32 s5, 10
	s_mov_b32 s93, 1
	s_mov_b32 s92, 2
	s_mov_b32 s86, 3
	s_mov_b32 s94, 0
	s_mov_b32 s80, 4
	s_mov_b32 s79, 5
	s_mov_b32 s78, 6
	s_mov_b32 s77, 7
	s_mov_b32 s76, 8
	s_mov_b32 s75, 9
	s_mov_b32 s74, 11
	s_mov_b32 s37, 12
	s_mov_b32 s4, 13
	s_mov_b32 s1, 14
	s_mov_b32 s0, 15
	s_branch .LBB0_513

; DI void s5_job(const Params& p, int l, int job, char* smem) {
;     ...
;       bf16x8 ua = ua_next;
;       {
;         const int cn = c + 1 < TPB / 16 ? c + 1 : c;
;         int tln;
;         if (d == 0) tln = 16 * cn;
;         else tln = cn < 16 ? (CTXL - 16 - 16 * cn) : (CTXL + SEQ - 16 - 16 * (cn - 16));
;         if (quad < 2) ua_next = *(const bf16x8*)(Pb + (size_t)(tln + col) * PW + 8 * quad);
;       }
.LBB0_511:
	s_lshl_b32 s37, s5, 4
	v_mov_b64_e32 v[48:49], v[52:53]
	v_mov_b64_e32 v[50:51], v[54:55]
	s_and_saveexec_b64 s[0:1], s[6:7]
	s_cbranch_execnz .LBB0_507
	s_branch .LBB0_508

; DI unsigned pack2(float a, float b) { f2 v = {a, b}; bf2 c = __builtin_convertvector(v, bf2); return __builtin_bit_cast(unsigned, c); }
; #define MFMA16(a, b, c) __builtin_amdgcn_mfma_f32_16x16x32_bf16((a), (b), (c), 0, 0, 0)
; #define WAVE_LDS_SYNC() do { __builtin_amdgcn_fence(__ATOMIC_RELEASE, "wavefront"); __builtin_amdgcn_wave_barrier(); __builtin_amdgcn_fence(__ATOMIC_ACQUIRE, "wavefront"); } while (0)
; DI void s5_job(const Params& p, int l, int job, char* smem) {
;     ...
; #pragma unroll
;       for (int nt = 0; nt < 8; ++nt) {
;         f32x4 z = {0.f, 0.f, 0.f, 0.f};
;         z = MFMA16(ua, bfr[nt], z);
; #pragma unroll
;         for (int q = 0; q < 4; ++q) Bu[(quad * 4 + q) * 128 + nt * 16 + col] = z[q];
;       }
;       WAVE_LDS_SYNC();
; #pragma unroll
;       for (int tt = 0; tt < 16; ++tt) {
;         const int t = d ? 15 - tt : tt;
;         float br = Bu[t * 128 + lane], bi = Bu[t * 128 + 64 + lane];
;         float nr = abr * xr - abi * xi + br;
;         float ni = abr * xi + abi * xr + bi;
;         xr = nr; xi = ni;
;         *(unsigned*)(Xs + t * 136 + 2 * lane) = pack2(xr, xi);
;       }
.LBB0_513:
	v_mfma_f32_16x16x32_bf16 v[106:109], v[52:55], v[16:19], 0
	v_add_u32_e32 v105, 0x400, v57
	v_lshl_add_u32 v126, s74, 9, v183
	v_lshl_add_u32 v128, s37, 9, v183
	v_mfma_f32_16x16x32_bf16 v[110:113], v[52:55], v[20:23], 0
	v_lshl_add_u32 v130, s4, 9, v183
	v_lshl_add_u32 v132, s1, 9, v183
	s_mulk_i32 s4, 0x110
	v_mfma_f32_16x16x32_bf16 v[114:117], v[52:55], v[24:27], 0
	v_add_u32_e32 v151, s4, v183
	s_nop 2
	ds_write2_b32 v57, v106, v110 offset1:16
	ds_write2_b32 v57, v107, v111 offset0:128 offset1:144
	v_mfma_f32_16x16x32_bf16 v[118:121], v[52:55], v[28:31], 0
	ds_write2_b32 v105, v108, v112 offset1:16
	ds_write2_b32 v105, v109, v113 offset0:128 offset1:144
	s_nop 5
	ds_write2_b32 v57, v114, v118 offset0:32 offset1:48
	ds_write2_b32 v57, v115, v119 offset0:160 offset1:176
	v_mfma_f32_16x16x32_bf16 v[122:125], v[52:55], v[32:35], 0
	v_lshl_add_u32 v114, s79, 9, v183
	s_mulk_i32 s79, 0x110
	v_add_u32_e32 v142, s79, v183
	v_mfma_f32_16x16x32_bf16 v[106:109], v[52:55], v[36:39], 0
	ds_write2_b32 v105, v116, v120 offset0:32 offset1:48
	ds_write2_b32 v105, v117, v121 offset0:160 offset1:176
	s_nop 5
	ds_write2_b32 v57, v122, v106 offset0:64 offset1:80
	ds_write2_b32 v57, v123, v107 offset0:192 offset1:208
	ds_write2_b32 v105, v124, v108 offset0:64 offset1:80
	ds_write2_b32 v105, v125, v109 offset0:192 offset1:208
	v_mfma_f32_16x16x32_bf16 v[110:113], v[52:55], v[40:43], 0
	v_lshl_add_u32 v106, s93, 9, v183
	v_lshl_add_u32 v108, s92, 9, v183
	s_mulk_i32 s93, 0x110
	v_mfma_f32_16x16x32_bf16 v[52:55], v[52:55], v[44:47], 0
	s_nop 7
	ds_write2_b32 v57, v110, v52 offset0:96 offset1:112
	ds_write2_b32 v57, v111, v53 offset0:224 offset1:240
	ds_write2_b32 v105, v112, v54 offset0:96 offset1:112
	ds_write2_b32 v105, v113, v55 offset0:224 offset1:240
	v_lshl_add_u32 v52, s94, 9, v183
	ds_read2st64_b32 v[52:53], v52 offset1:1
	v_pk_mul_f32 v[54:55], v[86:87], v[94:95]
	s_mulk_i32 s94, 0x110
	v_pk_fma_f32 v[136:137], v[88:89], v[94:95], v[54:55] op_sel:[0,0,1] op_sel_hi:[1,1,0] neg_lo:[0,0,1] neg_hi:[0,0,1]
	v_pk_fma_f32 v[54:55], v[88:89], v[94:95], v[54:55] op_sel:[0,0,1] op_sel_hi:[1,1,0]
	ds_read2st64_b32 v[106:107], v106 offset1:1
	v_mov_b32_e32 v137, v55
	s_waitcnt lgkmcnt(1)
	v_pk_add_f32 v[52:53], v[136:137], v[52:53]
	v_add_u32_e32 v105, s94, v183
	v_cvt_pk_bf16_f32 v54, v52, v53
	ds_write_b32 v105, v54 offset:8192
	v_pk_mul_f32 v[54:55], v[86:87], v[52:53]
	ds_read2st64_b32 v[108:109], v108 offset1:1
	v_pk_fma_f32 v[94:95], v[88:89], v[52:53], v[54:55] op_sel:[0,0,1] op_sel_hi:[1,1,0] neg_lo:[0,0,1] neg_hi:[0,0,1]
	v_pk_fma_f32 v[52:53], v[88:89], v[52:53], v[54:55] op_sel:[0,0,1] op_sel_hi:[1,1,0]
	v_add_u32_e32 v138, s93, v183
	v_mov_b32_e32 v95, v53
	s_waitcnt lgkmcnt(2)
	v_pk_add_f32 v[52:53], v[106:107], v[94:95]
	v_lshl_add_u32 v110, s86, 9, v183
	v_cvt_pk_bf16_f32 v54, v52, v53
	ds_write_b32 v138, v54 offset:8192
	v_pk_mul_f32 v[54:55], v[86:87], v[52:53]
	s_mulk_i32 s92, 0x110
	v_pk_fma_f32 v[94:95], v[88:89], v[52:53], v[54:55] op_sel:[0,0,1] op_sel_hi:[1,1,0] neg_lo:[0,0,1] neg_hi:[0,0,1]
	v_pk_fma_f32 v[52:53], v[88:89], v[52:53], v[54:55] op_sel:[0,0,1] op_sel_hi:[1,1,0]
	ds_read2st64_b32 v[110:111], v110 offset1:1
	v_mov_b32_e32 v95, v53
	s_waitcnt lgkmcnt(2)
	v_pk_add_f32 v[52:53], v[108:109], v[94:95]
	v_add_u32_e32 v139, s92, v183
	v_cvt_pk_bf16_f32 v54, v52, v53
	ds_write_b32 v139, v54 offset:8192
	v_pk_mul_f32 v[54:55], v[86:87], v[52:53]
	v_lshl_add_u32 v112, s80, 9, v183
	v_pk_fma_f32 v[94:95], v[88:89], v[52:53], v[54:55] op_sel:[0,0,1] op_sel_hi:[1,1,0] neg_lo:[0,0,1] neg_hi:[0,0,1]
	v_pk_fma_f32 v[52:53], v[88:89], v[52:53], v[54:55] op_sel:[0,0,1] op_sel_hi:[1,1,0]
	s_mulk_i32 s86, 0x110
	v_mov_b32_e32 v95, v53
	ds_read2st64_b32 v[112:113], v112 offset1:1
	s_waitcnt lgkmcnt(2)
	v_pk_add_f32 v[52:53], v[110:111], v[94:95]
	v_add_u32_e32 v140, s86, v183
	v_cvt_pk_bf16_f32 v54, v52, v53
	ds_write_b32 v140, v54 offset:8192
	v_pk_mul_f32 v[54:55], v[86:87], v[52:53]
	s_mulk_i32 s80, 0x110
	v_pk_fma_f32 v[94:95], v[88:89], v[52:53], v[54:55] op_sel:[0,0,1] op_sel_hi:[1,1,0] neg_lo:[0,0,1] neg_hi:[0,0,1]
	v_pk_fma_f32 v[52:53], v[88:89], v[52:53], v[54:55] op_sel:[0,0,1] op_sel_hi:[1,1,0]
	ds_read2st64_b32 v[114:115], v114 offset1:1
	v_mov_b32_e32 v95, v53
	s_waitcnt lgkmcnt(2)
	v_pk_add_f32 v[52:53], v[112:113], v[94:95]
	v_add_u32_e32 v141, s80, v183
	v_cvt_pk_bf16_f32 v54, v52, v53
	ds_write_b32 v141, v54 offset:8192
	v_pk_mul_f32 v[54:55], v[86:87], v[52:53]
	v_lshl_add_u32 v116, s78, 9, v183
	v_pk_fma_f32 v[94:95], v[88:89], v[52:53], v[54:55] op_sel:[0,0,1] op_sel_hi:[1,1,0] neg_lo:[0,0,1] neg_hi:[0,0,1]
	v_pk_fma_f32 v[52:53], v[88:89], v[52:53], v[54:55] op_sel:[0,0,1] op_sel_hi:[1,1,0]
	ds_read2st64_b32 v[116:117], v116 offset1:1
	v_mov_b32_e32 v95, v53
	s_waitcnt lgkmcnt(2)
	v_pk_add_f32 v[52:53], v[114:115], v[94:95]
	v_lshl_add_u32 v118, s77, 9, v183
	v_cvt_pk_bf16_f32 v54, v52, v53
	ds_write_b32 v142, v54 offset:8192
	v_pk_mul_f32 v[54:55], v[86:87], v[52:53]
	s_mulk_i32 s78, 0x110
	v_pk_fma_f32 v[94:95], v[88:89], v[52:53], v[54:55] op_sel:[0,0,1] op_sel_hi:[1,1,0] neg_lo:[0,0,1] neg_hi:[0,0,1]
	v_pk_fma_f32 v[52:53], v[88:89], v[52:53], v[54:55] op_sel:[0,0,1] op_sel_hi:[1,1,0]
	ds_read2st64_b32 v[118:119], v118 offset1:1
	v_mov_b32_e32 v95, v53
	s_waitcnt lgkmcnt(2)
	v_pk_add_f32 v[52:53], v[116:117], v[94:95]
	v_add_u32_e32 v143, s78, v183
	v_cvt_pk_bf16_f32 v54, v52, v53
	ds_write_b32 v143, v54 offset:8192
	v_pk_mul_f32 v[54:55], v[86:87], v[52:53]
	v_lshl_add_u32 v120, s76, 9, v183
	v_pk_fma_f32 v[94:95], v[88:89], v[52:53], v[54:55] op_sel:[0,0,1] op_sel_hi:[1,1,0] neg_lo:[0,0,1] neg_hi:[0,0,1]
	v_pk_fma_f32 v[52:53], v[88:89], v[52:53], v[54:55] op_sel:[0,0,1] op_sel_hi:[1,1,0]
	s_mulk_i32 s77, 0x110
	v_mov_b32_e32 v95, v53
	ds_read2st64_b32 v[120:121], v120 offset1:1
	s_waitcnt lgkmcnt(2)
; DI u16 f2bf(float f) { unsigned u = __float_as_uint(f); u += 0x7fffu + ((u >> 16) & 1u); return (u16)(u >> 16); }
; DI float bf2f(u16 v) { return __uint_as_float(((unsigned)v) << 16); }
; DI unsigned pack2(float a, float b) { f2 v = {a, b}; bf2 c = __builtin_convertvector(v, bf2); return __builtin_bit_cast(unsigned, c); }
; DI float tanh_fast(float x) { float e = __expf(2.f * x); return 1.f - 2.f * __builtin_amdgcn_rcpf(1.f + e); }
; #define MFMA16(a, b, c) __builtin_amdgcn_mfma_f32_16x16x32_bf16((a), (b), (c), 0, 0, 0)
; #define WAVE_LDS_SYNC() do { __builtin_amdgcn_fence(__ATOMIC_RELEASE, "wavefront"); __builtin_amdgcn_wave_barrier(); __builtin_amdgcn_fence(__ATOMIC_ACQUIRE, "wavefront"); } while (0)
; DI void s5_job(const Params& p, int l, int job, char* smem) {
;     ...
;       for (int tt = 0; tt < 16; ++tt) {
;         const int t = d ? 15 - tt : tt;
;         float br = Bu[t * 128 + lane], bi = Bu[t * 128 + 64 + lane];
;         float nr = abr * xr - abi * xi + br;
;         float ni = abr * xi + abi * xr + bi;
;         xr = nr; xi = ni;
;         *(unsigned*)(Xs + t * 136 + 2 * lane) = pack2(xr, xi);
;       }
;       WAVE_LDS_SYNC();
;       f32x4 y = {0.f, 0.f, 0.f, 0.f};
; #pragma unroll
;       for (int ks = 0; ks < 4; ++ks) {
;         bf16x8 a = *(const bf16x8*)(Xs + col * 136 + 32 * ks + 8 * quad);
;         y = MFMA16(a, cf[ks], y);
;       }
; #pragma unroll
;       for (int q = 0; q < 4; ++q) {
;         const int tok = tlo + quad * 4 + q;
;         if (pass == 0) {
;           Sb[(size_t)tok * 512 + col] = f2bf(y[q]);
;         } else {
;           float u = bf2f(pu[q]);
;           float v = y[q] + bf2f(psb[q]) + dsk * u;
;           float gl = 0.5f * v * (1.f + tanh_fast(0.7978845608028654f * (v + 0.044715f * v * v * v)));
;           Pb[(size_t)tok * PW + col] = f2bf(gl);
;         }
	v_pk_add_f32 v[52:53], v[118:119], v[94:95]
	v_add_u32_e32 v145, s77, v183
	v_cvt_pk_bf16_f32 v54, v52, v53
	ds_write_b32 v145, v54 offset:8192
	v_pk_mul_f32 v[54:55], v[86:87], v[52:53]
	v_lshl_add_u32 v122, s75, 9, v183
	v_pk_fma_f32 v[94:95], v[88:89], v[52:53], v[54:55] op_sel:[0,0,1] op_sel_hi:[1,1,0] neg_lo:[0,0,1] neg_hi:[0,0,1]
	v_pk_fma_f32 v[52:53], v[88:89], v[52:53], v[54:55] op_sel:[0,0,1] op_sel_hi:[1,1,0]
	s_mulk_i32 s76, 0x110
	v_mov_b32_e32 v95, v53
	ds_read2st64_b32 v[122:123], v122 offset1:1
	s_waitcnt lgkmcnt(2)
	v_pk_add_f32 v[52:53], v[120:121], v[94:95]
	v_add_u32_e32 v146, s76, v183
	v_cvt_pk_bf16_f32 v54, v52, v53
	ds_write_b32 v146, v54 offset:8192
	v_pk_mul_f32 v[54:55], v[86:87], v[52:53]
	v_lshl_add_u32 v124, s5, 9, v183
	v_pk_fma_f32 v[94:95], v[88:89], v[52:53], v[54:55] op_sel:[0,0,1] op_sel_hi:[1,1,0] neg_lo:[0,0,1] neg_hi:[0,0,1]
	v_pk_fma_f32 v[52:53], v[88:89], v[52:53], v[54:55] op_sel:[0,0,1] op_sel_hi:[1,1,0]
	s_mulk_i32 s75, 0x110
	v_mov_b32_e32 v95, v53
	ds_read2st64_b32 v[124:125], v124 offset1:1
	s_waitcnt lgkmcnt(2)
	v_pk_add_f32 v[52:53], v[122:123], v[94:95]
	v_add_u32_e32 v147, s75, v183
	v_cvt_pk_bf16_f32 v54, v52, v53
	ds_write_b32 v147, v54 offset:8192
	v_pk_mul_f32 v[54:55], v[86:87], v[52:53]
	s_mulk_i32 s5, 0x110
	v_pk_fma_f32 v[94:95], v[88:89], v[52:53], v[54:55] op_sel:[0,0,1] op_sel_hi:[1,1,0] neg_lo:[0,0,1] neg_hi:[0,0,1]
	v_pk_fma_f32 v[52:53], v[88:89], v[52:53], v[54:55] op_sel:[0,0,1] op_sel_hi:[1,1,0]
	ds_read2st64_b32 v[126:127], v126 offset1:1
	v_mov_b32_e32 v95, v53
	s_waitcnt lgkmcnt(2)
	v_pk_add_f32 v[52:53], v[124:125], v[94:95]
	v_add_u32_e32 v148, s5, v183
	v_cvt_pk_bf16_f32 v54, v52, v53
	ds_write_b32 v148, v54 offset:8192
	v_pk_mul_f32 v[54:55], v[86:87], v[52:53]
	s_mul_i32 s5, s74, 0x110
	v_pk_fma_f32 v[94:95], v[88:89], v[52:53], v[54:55] op_sel:[0,0,1] op_sel_hi:[1,1,0] neg_lo:[0,0,1] neg_hi:[0,0,1]
	v_pk_fma_f32 v[52:53], v[88:89], v[52:53], v[54:55] op_sel:[0,0,1] op_sel_hi:[1,1,0]
	ds_read2st64_b32 v[128:129], v128 offset1:1
	v_mov_b32_e32 v95, v53
	s_waitcnt lgkmcnt(2)
	v_pk_add_f32 v[52:53], v[126:127], v[94:95]
	v_add_u32_e32 v149, s5, v183
	v_cvt_pk_bf16_f32 v54, v52, v53
	ds_write_b32 v149, v54 offset:8192
	v_pk_mul_f32 v[54:55], v[86:87], v[52:53]
	s_mul_i32 s5, s37, 0x110
	v_pk_fma_f32 v[94:95], v[88:89], v[52:53], v[54:55] op_sel:[0,0,1] op_sel_hi:[1,1,0] neg_lo:[0,0,1] neg_hi:[0,0,1]
	v_pk_fma_f32 v[52:53], v[88:89], v[52:53], v[54:55] op_sel:[0,0,1] op_sel_hi:[1,1,0]
	ds_read2st64_b32 v[130:131], v130 offset1:1
	v_mov_b32_e32 v95, v53
	s_waitcnt lgkmcnt(2)
	v_pk_add_f32 v[52:53], v[128:129], v[94:95]
	v_add_u32_e32 v150, s5, v183
	v_cvt_pk_bf16_f32 v54, v52, v53
	ds_write_b32 v150, v54 offset:8192
	v_pk_mul_f32 v[54:55], v[86:87], v[52:53]
	ds_read2st64_b32 v[132:133], v132 offset1:1
	v_pk_fma_f32 v[94:95], v[88:89], v[52:53], v[54:55] op_sel:[0,0,1] op_sel_hi:[1,1,0] neg_lo:[0,0,1] neg_hi:[0,0,1]
	v_pk_fma_f32 v[52:53], v[88:89], v[52:53], v[54:55] op_sel:[0,0,1] op_sel_hi:[1,1,0]
	v_lshl_add_u32 v134, s0, 9, v183
	v_mov_b32_e32 v95, v53
	s_waitcnt lgkmcnt(2)
	v_pk_add_f32 v[52:53], v[130:131], v[94:95]
	s_mulk_i32 s1, 0x110
	v_cvt_pk_bf16_f32 v54, v52, v53
	ds_write_b32 v151, v54 offset:8192
	v_pk_mul_f32 v[54:55], v[86:87], v[52:53]
	ds_read2st64_b32 v[134:135], v134 offset1:1
	v_pk_fma_f32 v[94:95], v[88:89], v[52:53], v[54:55] op_sel:[0,0,1] op_sel_hi:[1,1,0] neg_lo:[0,0,1] neg_hi:[0,0,1]
	v_pk_fma_f32 v[52:53], v[88:89], v[52:53], v[54:55] op_sel:[0,0,1] op_sel_hi:[1,1,0]
	v_add_u32_e32 v152, s1, v183
	v_mov_b32_e32 v95, v53
	s_waitcnt lgkmcnt(2)
	v_pk_add_f32 v[52:53], v[132:133], v[94:95]
	s_mulk_i32 s0, 0x110
	v_cvt_pk_bf16_f32 v54, v52, v53
	ds_write_b32 v152, v54 offset:8192
	v_pk_mul_f32 v[54:55], v[86:87], v[52:53]
	s_and_b64 vcc, exec, s[8:9]
	v_pk_fma_f32 v[94:95], v[88:89], v[52:53], v[54:55] op_sel:[0,0,1] op_sel_hi:[1,1,0] neg_lo:[0,0,1] neg_hi:[0,0,1]
	v_pk_fma_f32 v[52:53], v[88:89], v[52:53], v[54:55] op_sel:[0,0,1] op_sel_hi:[1,1,0]
	s_nop 0
	v_mov_b32_e32 v95, v53
	s_waitcnt lgkmcnt(1)
	v_pk_add_f32 v[94:95], v[134:135], v[94:95]
	v_add_u32_e32 v53, s0, v183
	v_cvt_pk_bf16_f32 v52, v94, v95
	ds_write_b32 v53, v52 offset:8192
	ds_read_b128 v[52:55], v184 offset:8192
	ds_read_b128 v[106:109], v184 offset:8256
	s_waitcnt lgkmcnt(1)
	v_mfma_f32_16x16x32_bf16 v[52:55], v[52:55], v[0:3], 0
	ds_read_b128 v[110:113], v184 offset:8320
	s_mov_b64 s[0:1], -1
	s_waitcnt lgkmcnt(1)
	v_mfma_f32_16x16x32_bf16 v[52:55], v[106:109], v[4:7], v[52:55]
	ds_read_b128 v[106:109], v184 offset:8384
	s_waitcnt lgkmcnt(1)
	v_mfma_f32_16x16x32_bf16 v[52:55], v[110:113], v[8:11], v[52:55]
	s_waitcnt lgkmcnt(0)
	v_mfma_f32_16x16x32_bf16 v[52:55], v[106:109], v[12:15], v[52:55]
	s_cbranch_vccz .LBB0_515
	s_waitcnt vmcnt(0)
	v_lshlrev_b32_e32 v103, 16, v234
	v_lshlrev_b32_e32 v97, 16, v235
	v_lshlrev_b32_e32 v91, 16, v236
	v_lshlrev_b32_e32 v93, 16, v237
	v_lshlrev_b32_e32 v104, 16, v238
	v_lshlrev_b32_e32 v102, 16, v239
	v_lshlrev_b32_e32 v100, 16, v240
	v_lshlrev_b32_e32 v101, 16, v241
	v_add_f32_e32 v104, v104, v52
	v_fmac_f32_e32 v104, v182, v103
	v_mul_f32_e32 v105, 0x3d372713, v104
	v_mul_f32_e32 v105, v104, v105
	v_mul_f32_e32 v103, 0.5, v104
	v_fmac_f32_e32 v104, v104, v105
	v_mul_f32_e32 v104, 0x3f4c422a, v104
	v_add_f32_e32 v104, v104, v104
	v_mul_f32_e32 v104, 0x3fb8aa3b, v104
	v_exp_f32_e32 v104, v104
	s_mov_b64 s[0:1], 0
	v_add_f32_e32 v104, 1.0, v104
	v_rcp_f32_e32 v104, v104
	s_nop 0
	v_fma_f32 v104, v104, -2.0, 1.0
	v_add_f32_e32 v104, 1.0, v104
	v_mul_f32_e32 v103, v103, v104
	v_bfe_u32 v104, v103, 16, 1
	v_add3_u32 v103, v103, v104, s38
	v_mul_lo_u32 v104, v98, s81
	v_ashrrev_i32_e32 v105, 31, v104
	v_lshl_add_u64 v[104:105], v[64:65], 0, v[104:105]
	global_store_short_d16_hi v[104:105], v103, off

; DI void rwkv_job(const Params& p, int l, int job, char* smem) {
;     ...
;   __syncthreads();
;   if (tid < 64) {
;     const float* mu = p.rwkv_mu + l * 1792;
;     const int hc = h * 64 + tid;
;     cst[tid] = mu[PC_R + hc]; cst[64 + tid] = mu[PC_K + hc]; cst[128 + tid] = mu[PC_V + hc];
;     cst[192 + tid] = mu[PC_WD + tid]; cst[256 + tid] = mu[PC_AD + tid];
;     cst[320 + tid] = p.rwkv_k_k[l * 512 + hc]; cst[384 + tid] = p.rwkv_k_a[l * 512 + hc]; cst[448 + tid] = p.rwkv_r_k[l * 512 + hc];
;   }
; DI void phaseB(const Params& p, int l, char* smem) {
;     ...
;   if (slot == 0) {
;     const int job = fetch_job(p.ctr + l, &s_job);
;     if (job < NJ_RWKV) { __builtin_amdgcn_s_setprio(3); rwkv_job(p, l, job, smem); __builtin_amdgcn_s_setprio(0); }
.LBB0_537:
	s_or_b64 exec, exec, s[4:5]
	s_waitcnt lgkmcnt(0)
	s_barrier
	ds_read_b32 v0, v218
	s_movk_i32 s2, 0xff
	s_waitcnt lgkmcnt(0)
	v_cmp_lt_i32_e32 vcc, s2, v0
	v_readfirstlane_b32 s2, v0
	s_cbranch_vccnz .LBB0_601
	s_setprio 3
	v_mov_b32_e32 v2, v216
	s_bfe_u32 s34, s2, 0x30001
	s_nop 0
	v_cmp_lt_i32_e32 vcc, 63, v2
	s_barrier
	s_and_saveexec_b64 s[0:1], vcc
	s_xor_b64 s[0:1], exec, s[0:1]
	s_lshl_b32 s4, s34, 6
	s_or_saveexec_b64 s[0:1], s[0:1]
	v_mov_b32_e32 v4, s4
	s_xor_b64 exec, exec, s[0:1]
	s_cbranch_execz .LBB0_542
	s_ashr_i32 s97, s96, 31
	s_lshl_b64 s[4:5], s[96:97], 2
	s_add_u32 s4, s54, s4
	s_addc_u32 s5, s55, s5
	s_lshl_b32 s6, s34, 6
	v_add_u32_e32 v0, s6, v2
	v_ashrrev_i32_e32 v1, 31, v0
	v_lshl_add_u64 v[4:5], v[0:1], 2, s[4:5]
	global_load_dword v1, v[4:5], off
	global_load_dword v7, v[4:5], off offset:2048
	s_movk_i32 s7, 0x1000
	v_add_co_u32_e32 v4, vcc, s7, v4
	v_ashrrev_i32_e32 v3, 31, v2
	v_lshlrev_b32_e32 v6, 2, v2
	v_addc_co_u32_e32 v5, vcc, 0, v5, vcc
	v_readlane_b32 s8, v253, 6
	v_readlane_b32 s18, v253, 16
	v_readlane_b32 s19, v253, 17
	v_readlane_b32 s20, v253, 18
	v_readlane_b32 s21, v253, 19
	v_readlane_b32 s22, v253, 20
	v_readlane_b32 s23, v253, 21
	v_readlane_b32 s9, v253, 7
	v_readlane_b32 s10, v253, 8
	v_readlane_b32 s11, v253, 9
	v_readlane_b32 s12, v253, 10
	v_readlane_b32 s13, v253, 11
	v_readlane_b32 s14, v253, 12
	v_readlane_b32 s15, v253, 13
	v_readlane_b32 s16, v253, 14
	v_readlane_b32 s17, v253, 15
	s_waitcnt vmcnt(0)
	ds_write2st64_b32 v6, v1, v7 offset0:228 offset1:229
	global_load_dword v1, v[4:5], off
	v_lshl_add_u64 v[4:5], v[2:3], 2, s[4:5]
	v_add_co_u32_e32 v4, vcc, s7, v4
	v_readlane_b32 s4, v255, 44
	s_nop 0
	v_addc_co_u32_e32 v5, vcc, 0, v5, vcc
	global_load_dword v3, v[4:5], off offset:2048
	v_lshl_add_u32 v0, s4, 9, v0
	v_readlane_b32 s5, v255, 45
	s_waitcnt vmcnt(0)
	ds_write2st64_b32 v6, v1, v3 offset0:230 offset1:231
	v_ashrrev_i32_e32 v1, 31, v0
	v_lshlrev_b64 v[0:1], 2, v[0:1]
	global_load_dword v3, v[4:5], off offset:2304
	v_lshl_add_u64 v[4:5], s[18:19], 0, v[0:1]
	global_load_dword v4, v[4:5], off
	s_waitcnt vmcnt(0)
	ds_write2st64_b32 v6, v3, v4 offset0:232 offset1:233
	v_lshl_add_u64 v[4:5], s[20:21], 0, v[0:1]
	v_lshl_add_u64 v[0:1], s[22:23], 0, v[0:1]
	global_load_dword v3, v[4:5], off
	v_mov_b32_e32 v4, s6
	global_load_dword v0, v[0:1], off
	s_waitcnt vmcnt(0)
	ds_write2st64_b32 v6, v3, v0 offset0:234 offset1:235

; DI bool swz_tile(int i, int NC, int& rt, int& ct) {
;   const int G = gridDim.x;
;   if ((G & 7) == 0) {
;     const int x = blockIdx.x & 7, j = blockIdx.x >> 3, per = G >> 3;
;     const int T8 = NROWT * NC / 8;
;     const int ul = i * per + j;
;     if (ul >= T8) return false;
;     const int u = x * T8 + ul;
;     const int band = u / (8 * NC), rem = u % (8 * NC);
;     ct = rem >> 3; rt = band * 8 + (rem & 7);
;     return true;
;   }
.LBB0_955:
	s_mul_i32 s6, s37, s36
	v_readlane_b32 s4, v254, 18
	s_add_i32 s6, s6, s4
	v_readlane_b32 s4, v253, 2
	s_cmp_ge_i32 s4, 29
	s_cselect_b32 s4, 16, 0
	s_sub_i32 s4, 0x10f, s4
	s_cmp_gt_i32 s6, s4
	s_mov_b64 s[4:5], 0
	s_cbranch_scc1 .LBB0_957
	v_readlane_b32 s4, v254, 26
	v_readlane_b32 s5, v253, 2
	s_cmp_ge_i32 s5, 29
	s_cbranch_scc0 .Lctxsw4_a
	v_readlane_b32 s4, v254, 36
	s_and_b32 s4, s4, 7
	s_lshl_b32 s4, s4, 8
.Lctxsw4_a:
	s_add_i32 s4, s6, s4
	s_ashr_i32 s5, s4, 31
	s_lshr_b32 s5, s5, 26
	s_add_i32 s5, s4, s5
	s_ashr_i32 s6, s5, 6
	s_andn2_b32 s5, s5, 63
	s_sub_i32 s4, s4, s5
	s_ashr_i32 s9, s4, 3
	s_lshl_b32 s5, s6, 3
	s_and_b32 s4, s4, 7
	s_or_b32 s8, s4, s5
	v_readlane_b32 s5, v253, 2
	s_cmp_ge_i32 s5, 29
	s_cbranch_scc0 .Lctxsw4_b
	s_lshr_b32 s5, s8, 5
	s_lshl_b32 s5, s5, 1
	s_add_i32 s8, s8, s5
	s_add_i32 s8, s8, 2
.Lctxsw4_b:
	s_mov_b64 s[4:5], -1
.LBB0_957:
	s_mov_b32 s95, s8
	s_mov_b32 s94, s9
	s_andn2_b64 vcc, exec, s[4:5]
	s_mov_b64 s[4:5], -1
	s_cbranch_vccz .LBB0_874
